# v056 + grid barrier waits on the top arrival counter itself (no generation word hop)
# speedup vs baseline: 1.0059x; 1.0059x over previous
.LBB0_69:
	s_lshl_b32 s8, s3, 8
	s_add_u32 s8, s34, s8
	s_addc_u32 s9, s35, 0
	v_mov_b32_e32 v3, 0x1000
	v_mov_b32_e32 v5, 1
	global_atomic_add v5, v3, v5, s[8:9] offset:1024 sc0
	v_cvt_f32_u32_e32 v3, v4
	v_sub_u32_e32 v6, 0, v4
	v_rcp_iflag_f32_e32 v3, v3
	s_nop 0
	v_mul_f32_e32 v3, 0x4f7ffffe, v3
	v_cvt_u32_f32_e32 v3, v3
	v_mul_lo_u32 v6, v6, v3
	v_mul_hi_u32 v6, v3, v6
	v_add_u32_e32 v3, v3, v6
	s_waitcnt vmcnt(0)
	v_mul_hi_u32 v3, v5, v3
	v_mul_lo_u32 v6, v3, v4
	v_sub_u32_e32 v6, v5, v6
	v_add_u32_e32 v7, 1, v3
	v_cmp_ge_u32_e32 vcc, v6, v4
	v_add_u32_e32 v5, 1, v5
	s_nop 0
	v_cndmask_b32_e32 v3, v3, v7, vcc
	v_sub_u32_e32 v7, v6, v4
	v_cndmask_b32_e32 v6, v6, v7, vcc
	v_add_u32_e32 v7, 1, v3
	v_cmp_ge_u32_e32 vcc, v6, v4
	s_nop 1
	v_cndmask_b32_e32 v3, v3, v7, vcc
	v_mul_lo_u32 v6, v4, v3
	v_add_u32_e32 v4, v6, v4
	v_cmp_ne_u32_e32 vcc, v5, v4
	s_and_saveexec_b64 s[14:15], vcc
	s_xor_b64 s[14:15], exec, s[14:15]
	s_cbranch_execz .LBB0_83
	s_waitcnt lgkmcnt(0)
	v_mad_u32_u24 v6, v3, v2, v2
	s_add_u32 s20, s38, 0x1d6c5400
	s_addc_u32 s21, s39, 0
	v_mov_b32_e32 v2, 0
	s_mov_b32 s48, 0
.Lmy_bf_0:
	global_load_dword v4, v2, s[20:21] sc1
	s_waitcnt vmcnt(0)
	v_sub_u32_e32 v4, v4, v6
	v_cmp_gt_i32_e32 vcc, 0, v4
	s_cbranch_vccz .Lmy_bf_0d
	s_sleep 1
	s_add_i32 s48, s48, 1
	s_cmp_lt_u32 s48, 0x100000
	s_cbranch_scc1 .Lmy_bf_0
.Lmy_bf_0d:
	buffer_inv sc1
	s_waitcnt vmcnt(0)
.LBB0_83:
	s_andn2_saveexec_b64 s[14:15], s[14:15]
	s_cbranch_execz .LBB0_101
	buffer_wbl2 sc1
	s_waitcnt lgkmcnt(0)
	v_mad_u32_u24 v6, v3, v2, v2
	s_waitcnt vmcnt(0)
	v_mov_b32_e32 v4, 0x1d6c5000
	v_mov_b32_e32 v5, 1
	global_atomic_add v4, v5, s[38:39] offset:1024
	s_add_u32 s16, s38, 0x1d6c5400
	s_addc_u32 s17, s39, 0
	v_mov_b32_e32 v2, 0
	s_mov_b32 s48, 0
.Lmy_bl_0:
	global_load_dword v4, v2, s[16:17] sc1
	s_waitcnt vmcnt(0)
	v_sub_u32_e32 v4, v4, v6
	v_cmp_gt_i32_e32 vcc, 0, v4
	s_cbranch_vccz .Lmy_bl_0d
	s_sleep 1
	s_add_i32 s48, s48, 1
	s_cmp_lt_u32 s48, 0x100000
	s_cbranch_scc1 .Lmy_bl_0

.LBB0_451:
	s_lshl_b32 s8, s3, 8
	s_add_u32 s8, s34, s8
	s_addc_u32 s9, s35, 0
	v_mov_b32_e32 v3, 0x1000
	v_mov_b32_e32 v5, 1
	global_atomic_add v5, v3, v5, s[8:9] offset:1024 sc0
	v_cvt_f32_u32_e32 v3, v4
	v_sub_u32_e32 v6, 0, v4
	v_rcp_iflag_f32_e32 v3, v3
	s_nop 0
	v_mul_f32_e32 v3, 0x4f7ffffe, v3
	v_cvt_u32_f32_e32 v3, v3
	v_mul_lo_u32 v6, v6, v3
	v_mul_hi_u32 v6, v3, v6
	v_add_u32_e32 v3, v3, v6
	s_waitcnt vmcnt(0)
	v_mul_hi_u32 v3, v5, v3
	v_mul_lo_u32 v6, v3, v4
	v_sub_u32_e32 v6, v5, v6
	v_add_u32_e32 v7, 1, v3
	v_cmp_ge_u32_e32 vcc, v6, v4
	v_add_u32_e32 v5, 1, v5
	s_nop 0
	v_cndmask_b32_e32 v3, v3, v7, vcc
	v_sub_u32_e32 v7, v6, v4
	v_cndmask_b32_e32 v6, v6, v7, vcc
	v_add_u32_e32 v7, 1, v3
	v_cmp_ge_u32_e32 vcc, v6, v4
	s_nop 1
	v_cndmask_b32_e32 v3, v3, v7, vcc
	v_mul_lo_u32 v6, v4, v3
	v_add_u32_e32 v4, v6, v4
	v_cmp_ne_u32_e32 vcc, v5, v4
	s_and_saveexec_b64 s[10:11], vcc
	s_xor_b64 s[10:11], exec, s[10:11]
	s_cbranch_execz .LBB0_465
	s_waitcnt lgkmcnt(0)
	v_mad_u32_u24 v6, v3, v2, v2
	s_add_u32 s16, s38, 0x1d6c5400
	s_addc_u32 s17, s39, 0
	v_mov_b32_e32 v2, 0
	s_mov_b32 s44, 0
.Lmy_bf_4:
	global_load_dword v4, v2, s[16:17] sc1
	s_waitcnt vmcnt(0)
	v_sub_u32_e32 v4, v4, v6
	v_cmp_gt_i32_e32 vcc, 0, v4
	s_cbranch_vccz .Lmy_bf_4d
	s_sleep 1
	s_add_i32 s44, s44, 1
	s_cmp_lt_u32 s44, 0x100000
	s_cbranch_scc1 .Lmy_bf_4

.LBB0_465:
	s_andn2_saveexec_b64 s[10:11], s[10:11]
	s_cbranch_execz .LBB0_483
	buffer_wbl2 sc1
	s_waitcnt lgkmcnt(0)
	v_mad_u32_u24 v6, v3, v2, v2
	s_waitcnt vmcnt(0)
	v_mov_b32_e32 v4, 0x1d6c5000
	v_mov_b32_e32 v5, 1
	global_atomic_add v4, v5, s[38:39] offset:1024
	s_add_u32 s12, s38, 0x1d6c5400
	s_addc_u32 s13, s39, 0
	v_mov_b32_e32 v2, 0
	s_mov_b32 s44, 0
.Lmy_bl_4:
	global_load_dword v4, v2, s[12:13] sc1
	s_waitcnt vmcnt(0)
	v_sub_u32_e32 v4, v4, v6
	v_cmp_gt_i32_e32 vcc, 0, v4
	s_cbranch_vccz .Lmy_bl_4d
	s_sleep 1
	s_add_i32 s44, s44, 1
	s_cmp_lt_u32 s44, 0x100000
	s_cbranch_scc1 .Lmy_bl_4

.LBB0_1711:
	s_lshl_b32 s6, s3, 8
	s_add_u32 s6, s34, s6
	s_addc_u32 s7, s35, 0
	v_mov_b32_e32 v3, 0x1000
	v_mov_b32_e32 v5, 1
	global_atomic_add v5, v3, v5, s[6:7] offset:1024 sc0
	v_cvt_f32_u32_e32 v3, v4
	v_sub_u32_e32 v6, 0, v4
	v_rcp_iflag_f32_e32 v3, v3
	s_nop 0
	v_mul_f32_e32 v3, 0x4f7ffffe, v3
	v_cvt_u32_f32_e32 v3, v3
	v_mul_lo_u32 v6, v6, v3
	v_mul_hi_u32 v6, v3, v6
	v_add_u32_e32 v3, v3, v6
	s_waitcnt vmcnt(0)
	v_mul_hi_u32 v3, v5, v3
	v_mul_lo_u32 v6, v3, v4
	v_sub_u32_e32 v6, v5, v6
	v_add_u32_e32 v7, 1, v3
	v_cmp_ge_u32_e32 vcc, v6, v4
	v_add_u32_e32 v5, 1, v5
	s_nop 0
	v_cndmask_b32_e32 v3, v3, v7, vcc
	v_sub_u32_e32 v7, v6, v4
	v_cndmask_b32_e32 v6, v6, v7, vcc
	v_add_u32_e32 v7, 1, v3
	v_cmp_ge_u32_e32 vcc, v6, v4
	s_nop 1
	v_cndmask_b32_e32 v3, v3, v7, vcc
	v_mul_lo_u32 v6, v4, v3
	v_add_u32_e32 v4, v6, v4
	v_cmp_ne_u32_e32 vcc, v5, v4
	s_and_saveexec_b64 s[8:9], vcc
	s_xor_b64 s[8:9], exec, s[8:9]
	s_cbranch_execz .LBB0_1725
	s_waitcnt lgkmcnt(0)
	v_mad_u32_u24 v6, v3, v2, v2
	s_add_u32 s14, s38, 0x1d6c5400
	s_addc_u32 s15, s39, 0
	v_mov_b32_e32 v2, 0
	s_mov_b32 s28, 0
.Lmy_bf_16:
	global_load_dword v4, v2, s[14:15] sc1
	s_waitcnt vmcnt(0)
	v_sub_u32_e32 v4, v4, v6
	v_cmp_gt_i32_e32 vcc, 0, v4
	s_cbranch_vccz .Lmy_bf_16d
	s_sleep 1
	s_add_i32 s28, s28, 1
	s_cmp_lt_u32 s28, 0x100000
	s_cbranch_scc1 .Lmy_bf_16

.LBB0_1725:
	s_andn2_saveexec_b64 s[8:9], s[8:9]
	s_cbranch_execz .LBB0_1743
	buffer_wbl2 sc1
	s_waitcnt lgkmcnt(0)
	v_mad_u32_u24 v6, v3, v2, v2
	s_waitcnt vmcnt(0)
	v_mov_b32_e32 v4, 0x1d6c5000
	v_mov_b32_e32 v5, 1
	global_atomic_add v4, v5, s[38:39] offset:1024
	s_add_u32 s10, s38, 0x1d6c5400
	s_addc_u32 s11, s39, 0
	v_mov_b32_e32 v2, 0
	s_mov_b32 s28, 0
.Lmy_bl_16:
	global_load_dword v4, v2, s[10:11] sc1
	s_waitcnt vmcnt(0)
	v_sub_u32_e32 v4, v4, v6
	v_cmp_gt_i32_e32 vcc, 0, v4
	s_cbranch_vccz .Lmy_bl_16d
	s_sleep 1
	s_add_i32 s28, s28, 1
	s_cmp_lt_u32 s28, 0x100000
	s_cbranch_scc1 .Lmy_bl_16

.LBB0_2154:
	s_lshl_b32 s3, s3, 8
	s_add_u32 s6, s34, s3
	s_addc_u32 s7, s35, 0
	v_mov_b32_e32 v3, 0x1000
	v_mov_b32_e32 v5, 1
	global_atomic_add v5, v3, v5, s[6:7] offset:1024 sc0
	v_cvt_f32_u32_e32 v3, v4
	v_sub_u32_e32 v6, 0, v4
	v_rcp_iflag_f32_e32 v3, v3
	s_nop 0
	v_mul_f32_e32 v3, 0x4f7ffffe, v3
	v_cvt_u32_f32_e32 v3, v3
	v_mul_lo_u32 v6, v6, v3
	v_mul_hi_u32 v6, v3, v6
	v_add_u32_e32 v3, v3, v6
	s_waitcnt vmcnt(0)
	v_mul_hi_u32 v3, v5, v3
	v_mul_lo_u32 v6, v3, v4
	v_sub_u32_e32 v6, v5, v6
	v_add_u32_e32 v7, 1, v3
	v_cmp_ge_u32_e32 vcc, v6, v4
	v_add_u32_e32 v5, 1, v5
	s_nop 0
	v_cndmask_b32_e32 v3, v3, v7, vcc
	v_sub_u32_e32 v7, v6, v4
	v_cndmask_b32_e32 v6, v6, v7, vcc
	v_add_u32_e32 v7, 1, v3
	v_cmp_ge_u32_e32 vcc, v6, v4
	s_nop 1
	v_cndmask_b32_e32 v3, v3, v7, vcc
	v_mul_lo_u32 v6, v4, v3
	v_add_u32_e32 v4, v6, v4
	v_cmp_ne_u32_e32 vcc, v5, v4
	s_and_saveexec_b64 s[8:9], vcc
	s_xor_b64 s[8:9], exec, s[8:9]
	s_cbranch_execz .LBB0_2168
	s_waitcnt lgkmcnt(0)
	v_mad_u32_u24 v6, v3, v2, v2
	s_add_u32 s14, s38, 0x1d6c5400
	s_addc_u32 s15, s39, 0
	v_mov_b32_e32 v2, 0
	s_mov_b32 s3, 0
.Lmy_bf_20:
	global_load_dword v4, v2, s[14:15] sc1
	s_waitcnt vmcnt(0)
	v_sub_u32_e32 v4, v4, v6
	v_cmp_gt_i32_e32 vcc, 0, v4
	s_cbranch_vccz .Lmy_bf_20d
	s_sleep 1
	s_add_i32 s3, s3, 1
	s_cmp_lt_u32 s3, 0x100000
	s_cbranch_scc1 .Lmy_bf_20

.LBB0_2168:
	s_andn2_saveexec_b64 s[8:9], s[8:9]
	s_cbranch_execz .LBB0_2186
	buffer_wbl2 sc1
	s_waitcnt lgkmcnt(0)
	v_mad_u32_u24 v6, v3, v2, v2
	s_waitcnt vmcnt(0)
	v_mov_b32_e32 v4, 0x1d6c5000
	v_mov_b32_e32 v5, 1
	global_atomic_add v4, v5, s[38:39] offset:1024
	s_add_u32 s10, s38, 0x1d6c5400
	s_addc_u32 s11, s39, 0
	v_mov_b32_e32 v2, 0
	s_mov_b32 s3, 0
.Lmy_bl_20:
	global_load_dword v4, v2, s[10:11] sc1
	s_waitcnt vmcnt(0)
	v_sub_u32_e32 v4, v4, v6
	v_cmp_gt_i32_e32 vcc, 0, v4
	s_cbranch_vccz .Lmy_bl_20d
	s_sleep 1
	s_add_i32 s3, s3, 1
	s_cmp_lt_u32 s3, 0x100000
	s_cbranch_scc1 .Lmy_bl_20
